# stack + row-sum chain head merged (one VALU less per attention tile)
# baseline (speedup 1.0000x reference)
.Lattn_back_a:
	ds_read_b128 v[126:129], v186 offset:49152
	ds_read_b128 v[130:133], v186 offset:57344
	v_add_f32_e32 v98, v201, v199
	v_add_f32_e32 v98, v202, v98
	v_add_f32_e32 v98, v205, v98
	v_add_f32_e32 v98, v207, v98
	v_add_f32_e32 v98, v209, v98
	s_waitcnt lgkmcnt(1)
	v_mfma_f32_32x32x16_bf16 v[82:97], v[126:129], v[118:121], v[236:251]
	v_add_f32_e32 v98, v211, v98
	v_add_f32_e32 v98, v213, v98
	v_add_f32_e32 v98, v215, v98
	ds_read_b128 v[134:137], v187 offset:49152
	ds_read_b128 v[138:141], v187 offset:57344
	ds_read_b128 v[142:145], v188 offset:49152
	ds_read_b128 v[146:149], v188 offset:57344
	ds_read_b128 v[154:157], v189 offset:49152
	ds_read_b128 v[226:229], v189 offset:57344
	v_add_f32_e32 v98, v216, v98
	v_add_f32_e32 v98, v217, v98
	v_add_f32_e32 v98, v218, v98
	s_waitcnt lgkmcnt(6)
	v_mfma_f32_32x32x16_bf16 v[66:81], v[130:133], v[118:121], v[236:251]
	v_add_f32_e32 v98, v221, v98
	v_add_f32_e32 v98, v222, v98
	v_add_f32_e32 v98, v223, v98
	v_add_f32_e32 v98, v224, v98
	v_add_f32_e32 v98, v195, v98
	v_add_f32_e32 v98, v196, v98
	v_add_f32_e32 v98, v197, v98
	s_waitcnt lgkmcnt(5)
	v_mfma_f32_32x32x16_bf16 v[82:97], v[134:137], v[114:117], v[82:97]
	v_add_f32_e32 v98, v198, v98
	v_add_f32_e32 v98, v200, v98
	v_add_f32_e32 v98, v203, v98
	v_add_f32_e32 v98, v204, v98
	v_add_f32_e32 v98, v206, v98
	v_add_f32_e32 v98, v208, v98
	v_add_f32_e32 v98, v210, v98
	s_waitcnt lgkmcnt(4)
	v_mfma_f32_32x32x16_bf16 v[66:81], v[138:141], v[114:117], v[66:81]
	v_add_f32_e32 v98, v212, v98
	v_add_f32_e32 v98, v214, v98
	v_add_f32_e32 v98, v150, v98
	v_add_f32_e32 v98, v151, v98
	v_add_f32_e32 v98, v152, v98
	v_add_f32_e32 v219, v153, v98
	s_waitcnt lgkmcnt(3)
	v_mfma_f32_32x32x16_bf16 v[82:97], v[142:145], v[110:113], v[82:97]
	v_cvt_pk_bf16_f32 v134, v199, v201
	v_cvt_pk_bf16_f32 v135, v202, v205
	v_cvt_pk_bf16_f32 v136, v207, v209
	v_cvt_pk_bf16_f32 v137, v211, v213
	v_cvt_pk_bf16_f32 v138, v215, v216
	s_waitcnt lgkmcnt(2)
	v_mfma_f32_32x32x16_bf16 v[66:81], v[146:149], v[110:113], v[66:81]
	v_cvt_pk_bf16_f32 v139, v217, v218
	v_cvt_pk_bf16_f32 v140, v221, v222
	v_cvt_pk_bf16_f32 v141, v223, v224
	v_cvt_pk_bf16_f32 v126, v195, v196
	v_cvt_pk_bf16_f32 v127, v197, v198
	v_cvt_pk_bf16_f32 v128, v200, v203
	v_cvt_pk_bf16_f32 v129, v204, v206
	s_waitcnt lgkmcnt(1)
	v_mfma_f32_32x32x16_bf16 v[82:97], v[154:157], v[106:109], v[82:97]
	v_cvt_pk_bf16_f32 v130, v208, v210
	v_cvt_pk_bf16_f32 v131, v212, v214
	v_cvt_pk_bf16_f32 v132, v150, v151
	v_cvt_pk_bf16_f32 v133, v152, v153
	s_waitcnt lgkmcnt(0)
	v_mfma_f32_32x32x16_bf16 v[66:81], v[226:229], v[106:109], v[66:81]
	global_load_dwordx4 v[142:145], v160, s[12:13] offset:2048
	global_load_dwordx4 v[146:149], v252, s[12:13]
	global_load_dwordx4 v[154:157], v161, s[12:13] offset:2048
	s_and_saveexec_b64 s[2:3], s[8:9]
	s_cbranch_execz .LBB0_348
	ds_read2_b32 v[196:197], v194 offset1:1
	ds_read2_b32 v[198:199], v194 offset0:16 offset1:17
	ds_read2_b32 v[200:201], v194 offset0:18 offset1:19
	ds_read2_b32 v[202:203], v194 offset0:24 offset1:25
	ds_read2_b32 v[204:205], v194 offset0:26 offset1:27
	ds_read2_b32 v[206:207], v194 offset0:2 offset1:3
	ds_read2_b32 v[208:209], v194 offset0:8 offset1:9
	ds_read2_b32 v[210:211], v194 offset0:10 offset1:11
	s_waitcnt lgkmcnt(7)
	v_add_f32_e32 v82, v82, v196
	v_add_f32_e32 v83, v83, v197
	s_waitcnt lgkmcnt(3)
	v_add_f32_e32 v96, v96, v204
	v_add_f32_e32 v97, v97, v205
	v_add_f32_e32 v94, v94, v202
	v_add_f32_e32 v95, v95, v203
	v_add_f32_e32 v92, v92, v200
	v_add_f32_e32 v93, v93, v201
	v_add_f32_e32 v90, v90, v198
	v_add_f32_e32 v91, v91, v199
	s_waitcnt lgkmcnt(0)
	v_add_f32_e32 v88, v88, v210
	v_add_f32_e32 v89, v89, v211
	v_add_f32_e32 v86, v86, v208
	v_add_f32_e32 v87, v87, v209
	v_add_f32_e32 v84, v84, v206
	v_add_f32_e32 v85, v85, v207
	ds_read2_b32 v[196:197], v194 offset0:48 offset1:49
	ds_read2_b32 v[198:199], v194 offset0:50 offset1:51
	ds_read2_b32 v[200:201], v194 offset0:56 offset1:57
	ds_read2_b32 v[202:203], v194 offset0:58 offset1:59
	ds_read2_b32 v[204:205], v194 offset0:32 offset1:33
	ds_read2_b32 v[206:207], v194 offset0:34 offset1:35
	ds_read2_b32 v[208:209], v194 offset0:40 offset1:41
	ds_read2_b32 v[210:211], v194 offset0:42 offset1:43
	s_waitcnt lgkmcnt(4)
	v_add_f32_e32 v80, v80, v202
	v_add_f32_e32 v81, v81, v203
	v_add_f32_e32 v78, v78, v200
	v_add_f32_e32 v79, v79, v201
	v_add_f32_e32 v76, v76, v198
	v_add_f32_e32 v77, v77, v199
	v_add_f32_e32 v74, v74, v196
	v_add_f32_e32 v75, v75, v197
	s_waitcnt lgkmcnt(0)
	v_add_f32_e32 v72, v72, v210
	v_add_f32_e32 v73, v73, v211
	v_add_f32_e32 v70, v70, v208
	v_add_f32_e32 v71, v71, v209
	v_add_f32_e32 v68, v68, v206
	v_add_f32_e32 v69, v69, v207
	v_add_f32_e32 v66, v66, v204
	v_add_f32_e32 v67, v67, v205

.Lattn_back_b:
	ds_read_b128 v[126:129], v186 offset:32768
	ds_read_b128 v[130:133], v186 offset:40960
	ds_read_b128 v[134:137], v187 offset:32768
	ds_read_b128 v[138:141], v187 offset:40960
	v_add_f32_e32 v98, v214, v212
	v_add_f32_e32 v98, v216, v98
	v_add_f32_e32 v98, v218, v98
	v_add_f32_e32 v98, v204, v98
	v_add_f32_e32 v98, v206, v98
	v_add_f32_e32 v98, v208, v98
	s_waitcnt lgkmcnt(3)
	v_mfma_f32_32x32x16_bf16 v[82:97], v[126:129], v[118:121], v[236:251]
	v_add_f32_e32 v98, v210, v98
	v_add_f32_e32 v98, v196, v98
	v_add_f32_e32 v98, v198, v98
	v_add_f32_e32 v98, v200, v98
	v_add_f32_e32 v98, v202, v98
	v_add_f32_e32 v98, v222, v98
	v_add_f32_e32 v98, v224, v98
	s_waitcnt lgkmcnt(2)
	v_mfma_f32_32x32x16_bf16 v[66:81], v[130:133], v[118:121], v[236:251]
	v_add_f32_e32 v98, v227, v98
	ds_read_b128 v[126:129], v188 offset:32768
	ds_read_b128 v[142:145], v188 offset:40960
	ds_read_b128 v[146:149], v189 offset:32768
	ds_read_b128 v[154:157], v189 offset:40960
	v_add_f32_e32 v98, v229, v98
	v_add_f32_e32 v98, v213, v98
	v_add_f32_e32 v98, v215, v98
	v_add_f32_e32 v98, v217, v98
	v_add_f32_e32 v98, v221, v98
	s_waitcnt lgkmcnt(5)
	v_mfma_f32_32x32x16_bf16 v[82:97], v[134:137], v[114:117], v[82:97]
	v_add_f32_e32 v98, v205, v98
	v_add_f32_e32 v98, v207, v98
	v_add_f32_e32 v98, v209, v98
	v_add_f32_e32 v98, v211, v98
	v_add_f32_e32 v98, v197, v98
	v_add_f32_e32 v98, v199, v98
	v_add_f32_e32 v98, v201, v98
	s_waitcnt lgkmcnt(4)
	v_mfma_f32_32x32x16_bf16 v[66:81], v[138:141], v[114:117], v[66:81]
	v_add_f32_e32 v98, v203, v98
	v_add_f32_e32 v98, v223, v98
	v_add_f32_e32 v98, v226, v98
	v_add_f32_e32 v98, v228, v98
	v_add_f32_e32 v98, v230, v98
	s_waitcnt lgkmcnt(3)
	v_mfma_f32_32x32x16_bf16 v[82:97], v[126:129], v[110:113], v[82:97]
	v_cvt_pk_bf16_f32 v150, v212, v214
	v_cvt_pk_bf16_f32 v151, v216, v218
	v_cvt_pk_bf16_f32 v152, v204, v206
	v_cvt_pk_bf16_f32 v153, v208, v210
	v_cvt_pk_bf16_f32 v134, v196, v198
	v_cvt_pk_bf16_f32 v135, v200, v202
	v_cvt_pk_bf16_f32 v136, v222, v224
	s_waitcnt lgkmcnt(2)
	v_mfma_f32_32x32x16_bf16 v[66:81], v[142:145], v[110:113], v[66:81]
	v_cvt_pk_bf16_f32 v137, v227, v229
	v_cvt_pk_bf16_f32 v130, v213, v215
	v_cvt_pk_bf16_f32 v131, v217, v221
	v_cvt_pk_bf16_f32 v132, v205, v207
	v_cvt_pk_bf16_f32 v133, v209, v211
	v_cvt_pk_bf16_f32 v126, v197, v199
	v_cvt_pk_bf16_f32 v127, v201, v203
	s_waitcnt lgkmcnt(1)
	v_mfma_f32_32x32x16_bf16 v[82:97], v[146:149], v[106:109], v[82:97]
	v_cvt_pk_bf16_f32 v128, v223, v226
	v_cvt_pk_bf16_f32 v129, v228, v230
	s_waitcnt lgkmcnt(0)
	v_mfma_f32_32x32x16_bf16 v[66:81], v[154:157], v[106:109], v[66:81]
	s_add_u32 s100, s12, 0xa0000
	s_addc_u32 s101, s13, 0
	global_load_dwordx4 v[138:141], v160, s[100:101] offset:2048
	global_load_dwordx4 v[142:145], v252, s[100:101]
	global_load_dwordx4 v[154:157], v161, s[100:101] offset:2048
	s_add_u32 s12, s12, 0x140000
	s_addc_u32 s13, s13, 0
	s_and_saveexec_b64 s[2:3], s[8:9]
	s_cbranch_execz .LBB0_345
	ds_read2_b32 v[196:197], v194 offset0:64 offset1:65
	ds_read2_b32 v[198:199], v194 offset0:80 offset1:81
	ds_read2_b32 v[200:201], v194 offset0:82 offset1:83
	ds_read2_b32 v[202:203], v194 offset0:88 offset1:89
	ds_read2_b32 v[204:205], v194 offset0:90 offset1:91
	ds_read2_b32 v[206:207], v194 offset0:66 offset1:67
	ds_read2_b32 v[208:209], v194 offset0:72 offset1:73
	ds_read2_b32 v[210:211], v194 offset0:74 offset1:75
	s_waitcnt lgkmcnt(7)
	v_add_f32_e32 v82, v82, v196
	v_add_f32_e32 v83, v83, v197
	s_waitcnt lgkmcnt(3)
	v_add_f32_e32 v96, v96, v204
	v_add_f32_e32 v97, v97, v205
	v_add_f32_e32 v94, v94, v202
	v_add_f32_e32 v95, v95, v203
	v_add_f32_e32 v92, v92, v200
	v_add_f32_e32 v93, v93, v201
	v_add_f32_e32 v90, v90, v198
	v_add_f32_e32 v91, v91, v199
	s_waitcnt lgkmcnt(0)
	v_add_f32_e32 v88, v88, v210
	v_add_f32_e32 v89, v89, v211
	v_add_f32_e32 v86, v86, v208
	v_add_f32_e32 v87, v87, v209
	v_add_f32_e32 v84, v84, v206
	v_add_f32_e32 v85, v85, v207
	ds_read2_b32 v[196:197], v194 offset0:112 offset1:113
	ds_read2_b32 v[198:199], v194 offset0:114 offset1:115
	ds_read2_b32 v[200:201], v194 offset0:120 offset1:121
	ds_read2_b32 v[202:203], v194 offset0:122 offset1:123
	ds_read2_b32 v[204:205], v194 offset0:96 offset1:97
	ds_read2_b32 v[206:207], v194 offset0:98 offset1:99
	ds_read2_b32 v[208:209], v194 offset0:104 offset1:105
	ds_read2_b32 v[210:211], v194 offset0:106 offset1:107
	s_waitcnt lgkmcnt(4)
	v_add_f32_e32 v80, v80, v202
	v_add_f32_e32 v81, v81, v203
	v_add_f32_e32 v78, v78, v200
	v_add_f32_e32 v79, v79, v201
	v_add_f32_e32 v76, v76, v198
	v_add_f32_e32 v77, v77, v199
	v_add_f32_e32 v74, v74, v196
	v_add_f32_e32 v75, v75, v197
	s_waitcnt lgkmcnt(0)
	v_add_f32_e32 v72, v72, v210
	v_add_f32_e32 v73, v73, v211
	v_add_f32_e32 v70, v70, v208
	v_add_f32_e32 v71, v71, v209
	v_add_f32_e32 v68, v68, v206
	v_add_f32_e32 v69, v69, v207
	v_add_f32_e32 v66, v66, v204
	v_add_f32_e32 v67, v67, v205
	s_branch .LBB0_345
